# P6 row loop software-pipelined: next row's 8 loads issued at the top of the current row into spare registers, handed over at the back-edge after a counted wait; no load waits inside the body
# speedup vs baseline: 1.0032x; 1.0032x over previous
; __global__ void __launch_bounds__(NWAVES * 64, 2) hymba_fwd(Args args) {
;     ...
; #pragma unroll
;       for (int j = 0; j < 4; ++j) { g1[j] = *(const f32x4*)(args.in[17] + 4 * lane + 256 * j); g2[j] = *(const f32x4*)(args.in[18] + 4 * lane + 256 * j); }
;       for (int m = gw; m < MROWS; m += NGW) { const f32x4* xr = (const f32x4*)xrow_ptr(args, m) + lane; const v2u* mr = (const v2u*)(MIX + (size_t)m * DM) + lane;
;         f32x4 v[4], mx[4]; float s = 0.f;
; #pragma unroll
;         for (int j = 0; j < 4; ++j) { v[j] = __builtin_nontemporal_load(xr + 64 * j); const v2u w = __builtin_nontemporal_load(mr + 64 * j); mx[j] = (f32x4){bflo(w.x), bfhi(w.x), bflo(w.y), bfhi(w.y)};
.LBB0_548:
	s_or_b64 exec, exec, s[0:1]
	s_waitcnt lgkmcnt(0)
	v_mov_b32_e32 v0, v210
	s_barrier
	v_readlane_b32 s1, v255, 12
	v_readfirstlane_b32 s0, v0
	s_ashr_i32 s0, s0, 6
	s_add_i32 s1, s0, s1
	s_cmp_gt_i32 s1, 0xbfff
	s_cbranch_scc1 .LBB0_563
	v_and_b32_e32 v34, 63, v0
	v_lshlrev_b32_e32 v28, 4, v34
	global_load_dwordx4 v[0:3], v28, s[56:57] offset:3072
	global_load_dwordx4 v[4:7], v28, s[56:57] offset:2048
	global_load_dwordx4 v[8:11], v28, s[56:57] offset:1024
	global_load_dwordx4 v[12:15], v28, s[56:57]
	global_load_dwordx4 v[16:19], v28, s[54:55]
	global_load_dwordx4 v[20:23], v28, s[54:55] offset:1024
	global_load_dwordx4 v[24:27], v28, s[54:55] offset:2048
	s_nop 0
	global_load_dwordx4 v[28:31], v28, s[54:55] offset:3072
	v_readlane_b32 s6, v255, 12
	s_ashr_i32 s1, s0, 31
	s_ashr_i32 s4, s6, 31
	s_add_u32 s6, s0, s6
	s_addc_u32 s7, s1, s4
	s_lshl_b64 s[0:1], s[6:7], 11
	s_add_u32 s8, s70, s0
	s_addc_u32 s9, s71, s1
	s_ashr_i32 s35, s34, 31
	s_lshl_b64 s[10:11], s[34:35], 11
	v_mov_b32_e32 v33, 0
	v_lshlrev_b32_e32 v32, 3, v34
	s_add_u32 s12, s68, s0
	s_mov_b32 s5, 0
	s_mov_b32 s3, 0x7f00000
	v_mov_b32_e32 v56, 0x358637bd
	s_mov_b32 s16, 0xf800000
	v_mov_b32_e32 v57, 0x260
	s_movk_i32 s17, 0x7fff
	v_mov_b32_e32 v58, 0x3a800000
	v_lshlrev_b32_e32 v59, 4, v34
	v_lshl_add_u64 v[34:35], s[46:47], 0, v[32:33]
	s_addc_u32 s13, s69, s1
	v_mov_b32_e32 v60, 1
	s_waitcnt vmcnt(7)
	v_mov_b32_e32 v36, v1
	v_mov_b32_e32 v37, v3
	v_mov_b32_e32 v1, v2
	s_waitcnt vmcnt(6)
	v_mov_b32_e32 v2, v5
	v_mov_b32_e32 v3, v7
	v_mov_b32_e32 v5, v6
	s_waitcnt vmcnt(5)
	v_mov_b32_e32 v6, v9
	v_mov_b32_e32 v7, v11
	v_mov_b32_e32 v9, v10
	s_waitcnt vmcnt(4)
	v_mov_b32_e32 v10, v13
	v_mov_b32_e32 v11, v15
	v_mov_b32_e32 v13, v14
	v_lshl_add_u64 v[128:129], s[8:9], 0, v[32:33]
	v_add_co_u32_e32 v128, vcc, s3, v128
	s_nop 1
	v_addc_co_u32_e32 v129, vcc, 0, v129, vcc
	global_load_dwordx2 v[50:51], v[128:129], off nt
	global_load_dwordx2 v[52:53], v[128:129], off offset:512 nt
	global_load_dwordx2 v[54:55], v[128:129], off offset:1024 nt
	global_load_dwordx2 v[62:63], v[128:129], off offset:1536 nt
	s_add_i32 s100, s6, 0xffff8000
	s_cmp_lt_i32 s6, 0x8000
	s_cselect_b32 s101, s7, 0
	s_cselect_b32 s100, s6, s100
	s_cselect_b32 s99, s37, s39
	s_cselect_b32 s98, s36, s38
	s_lshl_b64 s[100:101], s[100:101], 12
	s_add_u32 s98, s98, s100
	s_addc_u32 s99, s99, s101
	global_load_dwordx4 v[38:41], v59, s[98:99] nt
	global_load_dwordx4 v[42:45], v59, s[98:99] offset:1024 nt
	global_load_dwordx4 v[46:49], v59, s[98:99] offset:2048 nt
	global_load_dwordx4 v[124:127], v59, s[98:99] offset:3072 nt
	s_waitcnt vmcnt(0)
	s_branch .LBB0_551
.LBB0_550:
	s_add_u32 s6, s6, s34
	s_addc_u32 s7, s7, s35
	s_add_u32 s8, s8, s10
	s_addc_u32 s9, s9, s11
	s_add_u32 s12, s12, s10
	s_addc_u32 s13, s13, s11
	s_cmp_gt_i32 s6, 0xbfff
	s_cbranch_scc1 .LBB0_563
	s_waitcnt vmcnt(8)
	v_mov_b64_e32 v[50:51], v[100:101]
	v_mov_b64_e32 v[52:53], v[102:103]
	v_mov_b64_e32 v[54:55], v[104:105]
	v_mov_b64_e32 v[62:63], v[106:107]
	v_mov_b64_e32 v[38:39], v[108:109]
	v_mov_b64_e32 v[40:41], v[110:111]
	v_mov_b64_e32 v[42:43], v[112:113]
	v_mov_b64_e32 v[44:45], v[114:115]
	v_mov_b64_e32 v[46:47], v[116:117]
	v_mov_b64_e32 v[48:49], v[118:119]
	v_mov_b64_e32 v[124:125], v[120:121]
	v_mov_b64_e32 v[126:127], v[122:123]
.LBB0_551:
	v_lshl_add_u64 v[14:15], s[8:9], 0, v[32:33]
	s_add_u32 s98, s6, s34
	s_addc_u32 s99, s7, s35
	s_cmp_gt_i32 s98, 0xbfff
	s_cbranch_scc1 .Lp6_nopf
	s_add_u32 s100, s8, s10
	s_addc_u32 s101, s9, s11
	v_lshl_add_u64 v[128:129], s[100:101], 0, v[32:33]
	v_add_co_u32_e32 v128, vcc, s3, v128
	s_nop 1
	v_addc_co_u32_e32 v129, vcc, 0, v129, vcc
	global_load_dwordx2 v[100:101], v[128:129], off nt
	global_load_dwordx2 v[102:103], v[128:129], off offset:512 nt
	global_load_dwordx2 v[104:105], v[128:129], off offset:1024 nt
	global_load_dwordx2 v[106:107], v[128:129], off offset:1536 nt
	s_add_i32 s100, s98, 0xffff8000
	s_cmp_lt_i32 s98, 0x8000
	s_cselect_b32 s101, s99, 0
	s_cselect_b32 s100, s98, s100
	s_cselect_b32 s99, s37, s39
	s_cselect_b32 s98, s36, s38
	s_lshl_b64 s[100:101], s[100:101], 12
	s_add_u32 s98, s98, s100
	s_addc_u32 s99, s99, s101
	global_load_dwordx4 v[108:111], v59, s[98:99] nt
	global_load_dwordx4 v[112:115], v59, s[98:99] offset:1024 nt
	global_load_dwordx4 v[116:119], v59, s[98:99] offset:2048 nt
	global_load_dwordx4 v[120:123], v59, s[98:99] offset:3072 nt
; __device__ __forceinline__ unsigned pk2(float lo, float hi) { return f2bf(lo) | (f2bf(hi) << 16); }
; __global__ void __launch_bounds__(NWAVES * 64, 2) hymba_fwd(Args args) {
;     ...
;         for (int j = 0; j < 4; ++j) { v[j] = __builtin_nontemporal_load(xr + 64 * j); const v2u w = __builtin_nontemporal_load(mr + 64 * j); mx[j] = (f32x4){bflo(w.x), bfhi(w.x), bflo(w.y), bfhi(w.y)};
;           s += (mx[j].x * mx[j].x + mx[j].y * mx[j].y) + (mx[j].z * mx[j].z + mx[j].w * mx[j].w); }
;         const float rs = 1.0f / sqrtf(wave_sum(s) * (1.0f / DM) + EPS); float s2 = 0.f;
;         v2u* orow = (v2u*)(X1B + (size_t)m * DM) + lane;
; #pragma unroll
;         for (int j = 0; j < 4; ++j) { v[j] = v[j] + mx[j] * rs * g1[j]; { v2u w; w.x = pk2(v[j].x, v[j].y); w.y = pk2(v[j].z, v[j].w); __builtin_nontemporal_store(w, orow + 64 * j); } s2 += (v[j].x * v[j].x + v[j].y * v[j].y) + (v[j].z * v[j].z + v[j].w * v[j].w); }
.Lp6_nopf:
	v_mov_b32_e32 v61, 0
	v_mov_b32_e32 v64, 0
	v_lshlrev_b32_e32 v66, 16, v50
	v_and_b32_e32 v67, 0xffff0000, v50
	v_lshlrev_b32_e32 v50, 16, v51
	v_and_b32_e32 v51, 0xffff0000, v51
	v_lshlrev_b32_e32 v68, 16, v52
	v_and_b32_e32 v69, 0xffff0000, v52
	v_lshlrev_b32_e32 v52, 16, v53
	v_and_b32_e32 v53, 0xffff0000, v53
	v_lshlrev_b32_e32 v70, 16, v54
	v_and_b32_e32 v71, 0xffff0000, v54
	v_lshlrev_b32_e32 v54, 16, v55
	v_and_b32_e32 v55, 0xffff0000, v55
	v_lshlrev_b32_e32 v72, 16, v62
	v_and_b32_e32 v73, 0xffff0000, v62
	v_lshlrev_b32_e32 v74, 16, v63
	v_and_b32_e32 v75, 0xffff0000, v63
	v_mul_f32_e32 v62, v67, v67
	v_mul_f32_e32 v63, v51, v51
	v_mul_f32_e32 v65, v69, v69
	v_mul_f32_e32 v76, v53, v53
	v_mul_f32_e32 v77, v71, v71
	v_mul_f32_e32 v78, v55, v55
	v_fmac_f32_e32 v62, v66, v66
	v_fmac_f32_e32 v63, v50, v50
	v_fmac_f32_e32 v65, v68, v68
	v_fmac_f32_e32 v76, v52, v52
	v_mul_f32_e32 v79, v73, v73
	v_mul_f32_e32 v80, v75, v75
	v_fmac_f32_e32 v77, v70, v70
	v_fmac_f32_e32 v78, v54, v54
	v_add_f32_e32 v62, v62, v63
	v_add_f32_e32 v63, v65, v76
	v_fmac_f32_e32 v79, v72, v72
	v_fmac_f32_e32 v80, v74, v74
	v_add_f32_e32 v65, v77, v78
	v_add_f32_e32 v62, v62, v63
	v_add_f32_e32 v76, v79, v80
	v_add_f32_e32 v62, v62, v65
	v_add_f32_e32 v62, v62, v76
	v_lshl_add_u64 v[76:77], s[12:13], 0, v[32:33]
	s_nop 0
	v_add_f32_dpp v62, v62, v62 quad_perm:[1,0,3,2] row_mask:0xf bank_mask:0xf bound_ctrl:1
	s_nop 1
	v_add_f32_dpp v62, v62, v62 quad_perm:[2,3,0,1] row_mask:0xf bank_mask:0xf bound_ctrl:1
	s_nop 1
	v_add_f32_dpp v62, v62, v62 row_half_mirror row_mask:0xf bank_mask:0xf bound_ctrl:1
	s_nop 1
	v_add_f32_dpp v62, v62, v62 row_mirror row_mask:0xf bank_mask:0xf bound_ctrl:1
	s_nop 1
	v_mov_b32_dpp v61, v62 row_bcast:15 row_mask:0xa bank_mask:0xf
	v_add_f32_e32 v61, v62, v61
	s_nop 1
	v_mov_b32_dpp v64, v61 row_bcast:31 row_mask:0xc bank_mask:0xf
	v_add_f32_e32 v61, v61, v64
	s_nop 0
	v_readlane_b32 s0, v61, 63
	s_nop 1
	v_fma_f32 v61, s0, v58, v56
	v_mul_f32_e32 v62, 0x4f800000, v61
	v_cmp_gt_f32_e32 vcc, s16, v61
	s_nop 1
	v_cndmask_b32_e32 v61, v61, v62, vcc
	v_sqrt_f32_e32 v62, v61
	s_nop 0
	v_add_u32_e32 v63, -1, v62
	v_add_u32_e32 v64, 1, v62
	v_fma_f32 v65, -v63, v62, v61
	v_fma_f32 v78, -v64, v62, v61
	v_cmp_ge_f32_e64 s[0:1], 0, v65
	s_nop 1
	v_cndmask_b32_e64 v62, v62, v63, s[0:1]
	v_cmp_lt_f32_e64 s[0:1], 0, v78
	s_nop 1
	v_cndmask_b32_e64 v62, v62, v64, s[0:1]
	v_mul_f32_e32 v63, 0x37800000, v62
	v_cndmask_b32_e32 v62, v62, v63, vcc
	v_cmp_class_f32_e32 vcc, v61, v57
	s_nop 1
	v_cndmask_b32_e32 v61, v62, v61, vcc
	v_div_scale_f32 v78, s[0:1], v61, v61, 1.0
	v_rcp_f32_e32 v79, v78
	v_div_scale_f32 v80, vcc, 1.0, v61, 1.0
	s_and_b32 s14, s6, 0x7f
	v_fma_f32 v81, -v78, v79, 1.0
	v_fmac_f32_e32 v79, v81, v79
	v_mul_f32_e32 v81, v80, v79
	v_fma_f32 v82, -v78, v81, v80
	v_fmac_f32_e32 v81, v82, v79
	v_fma_f32 v78, -v78, v81, v80
	v_div_fmas_f32 v78, v78, v79, v81
	v_div_fixup_f32 v78, v78, v61, 1.0
	v_pk_mul_f32 v[66:67], v[78:79], v[66:67] op_sel_hi:[0,1]
	v_pk_mul_f32 v[50:51], v[78:79], v[50:51] op_sel_hi:[0,1]
	v_pk_mul_f32 v[68:69], v[78:79], v[68:69] op_sel_hi:[0,1]
	v_pk_mul_f32 v[80:81], v[78:79], v[52:53] op_sel_hi:[0,1]
	v_pk_fma_f32 v[50:51], v[50:51], v[18:19], v[40:41]
	v_pk_fma_f32 v[52:53], v[66:67], v[16:17], v[38:39]
	v_pk_fma_f32 v[38:39], v[80:81], v[22:23], v[44:45]
	v_pk_fma_f32 v[40:41], v[68:69], v[20:21], v[42:43]
	v_and_b32_sdwa v43, v52, v60 dst_sel:DWORD dst_unused:UNUSED_PAD src0_sel:WORD_1 src1_sel:DWORD
	v_and_b32_sdwa v44, v51, v60 dst_sel:DWORD dst_unused:UNUSED_PAD src0_sel:WORD_1 src1_sel:DWORD
	v_and_b32_sdwa v45, v53, v60 dst_sel:DWORD dst_unused:UNUSED_PAD src0_sel:WORD_1 src1_sel:DWORD
	v_and_b32_sdwa v42, v50, v60 dst_sel:DWORD dst_unused:UNUSED_PAD src0_sel:WORD_1 src1_sel:DWORD
	v_mul_f32_e32 v61, v53, v53
	v_mul_f32_e32 v66, v51, v51
	v_add3_u32 v69, v52, v43, s17
	v_add3_u32 v43, v51, v44, s17
	v_add3_u32 v44, v53, v45, s17
	v_add3_u32 v42, v50, v42, s17
	v_fmac_f32_e32 v61, v52, v52
	v_fmac_f32_e32 v66, v50, v50
	v_and_b32_e32 v43, 0xffff0000, v43
	v_and_b32_e32 v44, 0xffff0000, v44
	v_add_f32_e32 v45, v61, v66
	v_or_b32_sdwa v43, v43, v42 dst_sel:DWORD dst_unused:UNUSED_PAD src0_sel:DWORD src1_sel:WORD_1
	v_or_b32_sdwa v42, v44, v69 dst_sel:DWORD dst_unused:UNUSED_PAD src0_sel:DWORD src1_sel:WORD_1
; __device__ __forceinline__ unsigned pk2(float lo, float hi) { return f2bf(lo) | (f2bf(hi) << 16); }
; __global__ void __launch_bounds__(NWAVES * 64, 2) hymba_fwd(Args args) {
;     ...
;         for (int j = 0; j < 4; ++j) { v[j] = v[j] + mx[j] * rs * g1[j]; { v2u w; w.x = pk2(v[j].x, v[j].y); w.y = pk2(v[j].z, v[j].w); __builtin_nontemporal_store(w, orow + 64 * j); } s2 += (v[j].x * v[j].x + v[j].y * v[j].y) + (v[j].z * v[j].z + v[j].w * v[j].w); }
;         const float rs2 = 1.0f / sqrtf(wave_sum(s2) * (1.0f / DM) + EPS);
;         v2u* o8 = (v2u*)(H + (size_t)m * DM) + lane;
;         const int sm = m & 127; int crowi = -1;
;         if (sm >= 126) crowi = 4 * (((m >> 7) + 1) % NGRP) + (sm - 126); else if (sm <= 1) crowi = 4 * (m >> 7) + 2 + sm;
	v_and_b32_sdwa v44, v39, v60 dst_sel:DWORD dst_unused:UNUSED_PAD src0_sel:WORD_1 src1_sel:DWORD
	v_and_b32_sdwa v61, v41, v60 dst_sel:DWORD dst_unused:UNUSED_PAD src0_sel:WORD_1 src1_sel:DWORD
	v_and_b32_sdwa v67, v38, v60 dst_sel:DWORD dst_unused:UNUSED_PAD src0_sel:WORD_1 src1_sel:DWORD
	v_and_b32_sdwa v68, v40, v60 dst_sel:DWORD dst_unused:UNUSED_PAD src0_sel:WORD_1 src1_sel:DWORD
	v_add3_u32 v44, v39, v44, s17
	v_add3_u32 v61, v41, v61, s17
	global_store_dwordx2 v[76:77], v[42:43], off nt
	v_add3_u32 v42, v40, v68, s17
	v_add3_u32 v43, v38, v67, s17
	v_and_b32_e32 v44, 0xffff0000, v44
	v_and_b32_e32 v61, 0xffff0000, v61
	v_or_b32_sdwa v43, v44, v43 dst_sel:DWORD dst_unused:UNUSED_PAD src0_sel:DWORD src1_sel:WORD_1
	v_or_b32_sdwa v42, v61, v42 dst_sel:DWORD dst_unused:UNUSED_PAD src0_sel:DWORD src1_sel:WORD_1
	global_store_dwordx2 v[76:77], v[42:43], off offset:512 nt
	v_mul_f32_e32 v42, v41, v41
	v_mul_f32_e32 v43, v39, v39
	v_fmac_f32_e32 v42, v40, v40
	v_fmac_f32_e32 v43, v38, v38
	v_add_f32_e32 v42, v42, v43
	v_add_f32_e32 v61, v45, v42
	v_pk_mul_f32 v[44:45], v[78:79], v[70:71] op_sel_hi:[0,1]
	v_pk_mul_f32 v[42:43], v[78:79], v[54:55] op_sel_hi:[0,1]
	v_pk_fma_f32 v[46:47], v[44:45], v[24:25], v[46:47]
	v_pk_fma_f32 v[42:43], v[42:43], v[26:27], v[48:49]
	v_and_b32_sdwa v45, v46, v60 dst_sel:DWORD dst_unused:UNUSED_PAD src0_sel:WORD_1 src1_sel:DWORD
	v_add3_u32 v48, v46, v45, s17
	v_and_b32_sdwa v45, v43, v60 dst_sel:DWORD dst_unused:UNUSED_PAD src0_sel:WORD_1 src1_sel:DWORD
	v_and_b32_sdwa v49, v47, v60 dst_sel:DWORD dst_unused:UNUSED_PAD src0_sel:WORD_1 src1_sel:DWORD
	v_and_b32_sdwa v44, v42, v60 dst_sel:DWORD dst_unused:UNUSED_PAD src0_sel:WORD_1 src1_sel:DWORD
	v_add3_u32 v45, v43, v45, s17
	v_add3_u32 v49, v47, v49, s17
	v_add3_u32 v44, v42, v44, s17
	v_and_b32_e32 v45, 0xffff0000, v45
	v_and_b32_e32 v49, 0xffff0000, v49
	v_or_b32_sdwa v45, v45, v44 dst_sel:DWORD dst_unused:UNUSED_PAD src0_sel:DWORD src1_sel:WORD_1
	v_or_b32_sdwa v44, v49, v48 dst_sel:DWORD dst_unused:UNUSED_PAD src0_sel:DWORD src1_sel:WORD_1
	global_store_dwordx2 v[76:77], v[44:45], off offset:1024 nt
	v_mul_f32_e32 v44, v47, v47
	v_mul_f32_e32 v45, v43, v43
	v_fmac_f32_e32 v44, v46, v46
	v_fmac_f32_e32 v45, v42, v42
	v_add_f32_e32 v44, v44, v45
	v_pk_mul_f32 v[48:49], v[78:79], v[72:73] op_sel_hi:[0,1]
	v_add_f32_e32 v61, v61, v44
	v_pk_mul_f32 v[44:45], v[78:79], v[74:75] op_sel_hi:[0,1]
	v_pk_fma_f32 v[48:49], v[48:49], v[28:29], v[124:125]
	v_pk_fma_f32 v[44:45], v[44:45], v[30:31], v[126:127]
	v_and_b32_sdwa v55, v48, v60 dst_sel:DWORD dst_unused:UNUSED_PAD src0_sel:WORD_1 src1_sel:DWORD
	v_add3_u32 v62, v48, v55, s17
	v_and_b32_sdwa v55, v45, v60 dst_sel:DWORD dst_unused:UNUSED_PAD src0_sel:WORD_1 src1_sel:DWORD
	v_and_b32_sdwa v63, v49, v60 dst_sel:DWORD dst_unused:UNUSED_PAD src0_sel:WORD_1 src1_sel:DWORD
	v_and_b32_sdwa v54, v44, v60 dst_sel:DWORD dst_unused:UNUSED_PAD src0_sel:WORD_1 src1_sel:DWORD
	v_add3_u32 v55, v45, v55, s17
	v_add3_u32 v63, v49, v63, s17
	v_add3_u32 v54, v44, v54, s17
	v_and_b32_e32 v55, 0xffff0000, v55
	v_and_b32_e32 v63, 0xffff0000, v63
	v_or_b32_sdwa v55, v55, v54 dst_sel:DWORD dst_unused:UNUSED_PAD src0_sel:DWORD src1_sel:WORD_1
	v_or_b32_sdwa v54, v63, v62 dst_sel:DWORD dst_unused:UNUSED_PAD src0_sel:DWORD src1_sel:WORD_1
	global_store_dwordx2 v[76:77], v[54:55], off offset:1536 nt
	v_mul_f32_e32 v54, v49, v49
	v_mul_f32_e32 v55, v45, v45
	v_fmac_f32_e32 v54, v48, v48
	v_fmac_f32_e32 v55, v44, v44
	v_add_f32_e32 v54, v54, v55
	v_add_f32_e32 v54, v61, v54
	v_mov_b32_e32 v55, 0
	s_cmpk_lt_u32 s14, 0x7e
	v_add_f32_dpp v54, v54, v54 quad_perm:[1,0,3,2] row_mask:0xf bank_mask:0xf bound_ctrl:1
	s_mov_b64 s[0:1], -1
	s_nop 0
	v_add_f32_dpp v54, v54, v54 quad_perm:[2,3,0,1] row_mask:0xf bank_mask:0xf bound_ctrl:1
	s_nop 1
	v_add_f32_dpp v54, v54, v54 row_half_mirror row_mask:0xf bank_mask:0xf bound_ctrl:1
	s_nop 1
	v_add_f32_dpp v54, v54, v54 row_mirror row_mask:0xf bank_mask:0xf bound_ctrl:1
	s_nop 1
	v_mov_b32_dpp v55, v54 row_bcast:15 row_mask:0xa bank_mask:0xf
	v_add_f32_e32 v54, v54, v55
	v_mov_b32_e32 v55, 0
	s_nop 1
	v_mov_b32_dpp v55, v54 row_bcast:31 row_mask:0xc bank_mask:0xf
	v_add_f32_e32 v54, v54, v55
	s_nop 0
	v_readlane_b32 s4, v54, 63
	s_cbranch_scc0 .LBB0_553
	s_ashr_i32 s0, s6, 5
	s_and_b32 s0, s0, -4
	s_or_b32 s0, s14, s0
	s_or_b32 s0, s0, 2
	s_cmp_lt_u32 s14, 2
	s_cselect_b32 s18, s0, -1
	s_mov_b64 s[0:1], 0
